# P0: RMSNorm row loop software-prefetches the next iteration's two rows (8 loads) into spare VGPRs before computing the current
# baseline (speedup 1.0000x reference)
.Lmy_p0_b43:
	s_mov_b32 s77, 0
	v_mov_b32_e32 v35, 0
	v_mov_b32_e32 v37, v35
	v_lshl_add_u64 v[2:3], s[16:17], 0, v[36:37]
	s_mov_b64 s[0:1], 0x3a00000
	v_lshl_add_u64 v[40:41], v[2:3], 0, s[0:1]
	s_lshl_b32 s0, s33, 4
	s_ashr_i32 s5, s4, 31
	s_ashr_i32 s1, s0, 31
	v_lshl_add_u64 v[38:39], s[8:9], 0, v[34:35]
	global_load_dwordx4 v[88:91], v[38:39], off
	global_load_dwordx4 v[92:95], v[38:39], off offset:1024
	global_load_dwordx4 v[96:99], v[38:39], off offset:2048
	global_load_dwordx4 v[100:103], v[38:39], off offset:3072
	s_lshl_b64 s[6:7], s[4:5], 10
	s_lshl_b64 s[8:9], s[0:1], 10
	s_lshl_b64 s[2:3], s[4:5], 12
	s_add_u32 s10, s14, s2
	s_addc_u32 s11, s15, s3
	s_lshl_b64 s[18:19], s[0:1], 12
	s_lshl_b64 s[2:3], s[4:5], 11
	s_add_u32 s20, s16, s2
	s_addc_u32 s21, s17, s3
	s_add_i32 s2, s4, s25
	s_ashr_i32 s3, s2, 31
	s_lshl_b64 s[22:23], s[0:1], 11
	s_lshl_b64 s[26:27], s[2:3], 11
	s_add_u32 s16, s16, s26
	v_mbcnt_lo_u32_b32 v1, -1, 0
	s_addc_u32 s17, s17, s27
	s_lshl_b64 s[2:3], s[2:3], 12
	v_mbcnt_hi_u32_b32 v1, -1, v1
	s_add_u32 s14, s14, s2
	v_and_b32_e32 v2, 64, v1
	s_addc_u32 s15, s15, s3
	v_mov_b32_e32 v42, 0x358637bd
	s_mov_b32 s24, 0x3a800000
	s_mov_b32 s1, 0x800000
	s_mov_b32 s5, 0xffff0000
	s_mov_b32 s29, 0x3a00000
	v_add_u32_e32 v43, 64, v2
	v_xor_b32_e32 v46, 1, v1
	v_xor_b32_e32 v47, 2, v1
	v_xor_b32_e32 v48, 4, v1
	v_xor_b32_e32 v49, 8, v1
	v_xor_b32_e32 v50, 16, v1
	v_xor_b32_e32 v51, 32, v1
	v_mov_b32_e32 v52, 1
	s_branch .LBB0_45

.LBB0_47:
	s_andn2_b64 vcc, exec, s[2:3]
	s_mov_b64 s[2:3], s[6:7]
	s_cbranch_vccnz .LBB0_44
	s_cmp_lg_u32 s77, 0
	s_cbranch_scc1 .Lmy_p0_pfok
	global_load_dwordx4 v[104:107], v34, s[10:11]
	global_load_dwordx4 v[108:111], v34, s[10:11] offset:1024
	global_load_dwordx4 v[112:115], v34, s[10:11] offset:3072
	global_load_dwordx4 v[116:119], v34, s[10:11] offset:2048
	global_load_dwordx4 v[120:123], v34, s[14:15]
	global_load_dwordx4 v[124:127], v34, s[14:15] offset:1024
	global_load_dwordx4 v[128:131], v34, s[14:15] offset:3072
	global_load_dwordx4 v[132:135], v34, s[14:15] offset:2048
	s_waitcnt vmcnt(0)
.Lmy_p0_pfok:
	s_waitcnt vmcnt(8)
	v_mov_b32_e32 v30, v104
	v_mov_b32_e32 v31, v105
	v_mov_b32_e32 v32, v106
	v_mov_b32_e32 v33, v107
	v_mov_b32_e32 v22, v108
	v_mov_b32_e32 v23, v109
	v_mov_b32_e32 v24, v110
	v_mov_b32_e32 v25, v111
	v_mov_b32_e32 v6, v112
	v_mov_b32_e32 v7, v113
	v_mov_b32_e32 v8, v114
	v_mov_b32_e32 v9, v115
	v_mov_b32_e32 v14, v116
	v_mov_b32_e32 v15, v117
	v_mov_b32_e32 v16, v118
	v_mov_b32_e32 v17, v119
	v_mov_b32_e32 v26, v120
	v_mov_b32_e32 v27, v121
	v_mov_b32_e32 v28, v122
	v_mov_b32_e32 v29, v123
	v_mov_b32_e32 v18, v124
	v_mov_b32_e32 v19, v125
	v_mov_b32_e32 v20, v126
	v_mov_b32_e32 v21, v127
	v_mov_b32_e32 v2, v128
	v_mov_b32_e32 v3, v129
	v_mov_b32_e32 v4, v130
	v_mov_b32_e32 v5, v131
	v_mov_b32_e32 v10, v132
	v_mov_b32_e32 v11, v133
	v_mov_b32_e32 v12, v134
	v_mov_b32_e32 v13, v135
	s_mov_b32 s77, 0
	s_add_i32 s76, s4, s0
	s_cmp_lt_i32 s76, s62
	s_cbranch_scc0 .Lmy_p0_nopf
	s_add_i32 s76, s76, s25
	s_cmpk_gt_i32 s76, 0x7fff
	s_cbranch_scc1 .Lmy_p0_nopf
	s_add_u32 s80, s10, s18
	s_addc_u32 s81, s11, s19
	s_add_u32 s82, s14, s18
	s_addc_u32 s83, s15, s19
	global_load_dwordx4 v[104:107], v34, s[80:81]
	global_load_dwordx4 v[108:111], v34, s[80:81] offset:1024
	global_load_dwordx4 v[112:115], v34, s[80:81] offset:3072
	global_load_dwordx4 v[116:119], v34, s[80:81] offset:2048
	global_load_dwordx4 v[120:123], v34, s[82:83]
	global_load_dwordx4 v[124:127], v34, s[82:83] offset:1024
	global_load_dwordx4 v[128:131], v34, s[82:83] offset:3072
	global_load_dwordx4 v[132:135], v34, s[82:83] offset:2048
	s_mov_b32 s77, 1
.Lmy_p0_nopf:
	v_cmp_lt_i32_e32 vcc, v46, v43
	s_ashr_i32 s27, s26, 31
	v_cndmask_b32_e32 v53, v1, v46, vcc
	v_lshlrev_b32_e32 v53, 2, v53
	v_cmp_lt_i32_e32 vcc, v47, v43
	v_pk_mul_f32 v[58:59], v[32:33], v[32:33]
	v_pk_mul_f32 v[60:61], v[30:31], v[30:31]
	v_pk_mul_f32 v[62:63], v[24:25], v[24:25]
	v_pk_mul_f32 v[64:65], v[22:23], v[22:23]
	v_mul_f32_e32 v66, v15, v15
	v_mul_f32_e32 v68, v17, v17
	v_pk_mov_b32 v[70:71], v[60:61], v[58:59] op_sel:[1,0]
	v_mov_b32_e32 v61, v59
	v_pk_mul_f32 v[58:59], v[28:29], v[28:29]
	v_pk_mul_f32 v[72:73], v[26:27], v[26:27]
	v_pk_mov_b32 v[74:75], v[64:65], v[62:63] op_sel:[1,0]
	v_mov_b32_e32 v65, v63
	v_pk_mul_f32 v[62:63], v[20:21], v[20:21]
	v_pk_mul_f32 v[76:77], v[18:19], v[18:19]
	v_mul_f32_e32 v82, v8, v8
	v_mul_f32_e32 v83, v9, v9
	v_pk_fma_f32 v[66:67], v[14:15], v[14:15], v[66:67] op_sel_hi:[1,1,0]
	v_pk_fma_f32 v[68:69], v[16:17], v[16:17], v[68:69] op_sel_hi:[1,1,0]
	v_pk_add_f32 v[60:61], v[70:71], v[60:61]
	v_pk_mov_b32 v[70:71], v[72:73], v[58:59] op_sel:[1,0]
	v_mov_b32_e32 v73, v59
	v_pk_add_f32 v[58:59], v[74:75], v[64:65]
	v_pk_mov_b32 v[64:65], v[76:77], v[62:63] op_sel:[1,0]
	v_mov_b32_e32 v77, v63
	v_mul_f32_e32 v79, v6, v6
	v_mul_f32_e32 v81, v7, v7
	v_mul_f32_e32 v78, v11, v11
	v_mul_f32_e32 v80, v13, v13
	v_mov_b32_e32 v67, v82
	v_mov_b32_e32 v69, v83
	v_pk_add_f32 v[70:71], v[70:71], v[72:73]
	v_pk_add_f32 v[64:65], v[64:65], v[76:77]
	v_mul_f32_e32 v84, v2, v2
	v_mul_f32_e32 v85, v3, v3
	v_mul_f32_e32 v86, v4, v4
	v_mul_f32_e32 v87, v5, v5
	v_pk_fma_f32 v[62:63], v[10:11], v[10:11], v[78:79] op_sel_hi:[1,1,0]
	v_pk_fma_f32 v[74:75], v[12:13], v[12:13], v[80:81] op_sel_hi:[1,1,0]
	v_pk_add_f32 v[60:61], v[60:61], v[60:61] op_sel:[0,1] op_sel_hi:[1,0]
	v_pk_add_f32 v[58:59], v[58:59], v[58:59] op_sel:[0,1] op_sel_hi:[1,0]
	v_pk_add_f32 v[66:67], v[66:67], v[68:69]
	v_pk_add_f32 v[68:69], v[70:71], v[70:71] op_sel:[0,1] op_sel_hi:[1,0]
	v_pk_add_f32 v[64:65], v[64:65], v[64:65] op_sel:[0,1] op_sel_hi:[1,0]
	v_mov_b32_e32 v63, v86
	v_mov_b32_e32 v75, v87
	v_mov_b32_e32 v61, v79
	v_mov_b32_e32 v59, v81
	v_mov_b32_e32 v69, v84
	v_mov_b32_e32 v65, v85
	v_pk_add_f32 v[62:63], v[62:63], v[74:75]
	v_pk_add_f32 v[58:59], v[60:61], v[58:59]
	v_pk_add_f32 v[60:61], v[68:69], v[64:65]
	v_pk_add_f32 v[58:59], v[58:59], v[66:67]
	v_pk_add_f32 v[60:61], v[60:61], v[62:63]
	v_mov_b32_e32 v63, v58
	v_mov_b32_e32 v62, v60
	v_mov_b32_e32 v58, v61
	v_pk_add_f32 v[58:59], v[62:63], v[58:59]
	ds_bpermute_b32 v61, v53, v59
	ds_bpermute_b32 v60, v53, v58
	v_cndmask_b32_e32 v53, v1, v47, vcc
	v_lshlrev_b32_e32 v53, 2, v53
	v_cmp_lt_i32_e32 vcc, v48, v43
	s_waitcnt lgkmcnt(0)
	v_pk_add_f32 v[58:59], v[58:59], v[60:61]
	ds_bpermute_b32 v61, v53, v59
	ds_bpermute_b32 v60, v53, v58
	v_cndmask_b32_e32 v53, v1, v48, vcc
	v_lshlrev_b32_e32 v53, 2, v53
	v_cmp_lt_i32_e32 vcc, v49, v43
	s_waitcnt lgkmcnt(0)
	v_pk_add_f32 v[58:59], v[58:59], v[60:61]
	ds_bpermute_b32 v61, v53, v59
	ds_bpermute_b32 v60, v53, v58
	v_cndmask_b32_e32 v53, v1, v49, vcc
	v_lshlrev_b32_e32 v53, 2, v53
	v_cmp_lt_i32_e32 vcc, v50, v43
	s_waitcnt lgkmcnt(0)
	v_pk_add_f32 v[58:59], v[58:59], v[60:61]
	ds_bpermute_b32 v61, v53, v59
	ds_bpermute_b32 v60, v53, v58
	v_cndmask_b32_e32 v53, v1, v50, vcc
	v_lshlrev_b32_e32 v53, 2, v53
	v_cmp_lt_i32_e32 vcc, v51, v43
	s_waitcnt lgkmcnt(0)
	v_pk_add_f32 v[58:59], v[58:59], v[60:61]
	ds_bpermute_b32 v61, v53, v59
	ds_bpermute_b32 v60, v53, v58
	v_cndmask_b32_e32 v53, v1, v51, vcc
	v_lshlrev_b32_e32 v53, 2, v53
	s_waitcnt lgkmcnt(0)
	v_pk_add_f32 v[58:59], v[58:59], v[60:61]
	ds_bpermute_b32 v61, v53, v59
	ds_bpermute_b32 v60, v53, v58
	s_waitcnt lgkmcnt(0)
	v_pk_add_f32 v[58:59], v[58:59], v[60:61]
	s_nop 0
	v_pk_fma_f32 v[58:59], v[58:59], s[24:25], v[42:43] op_sel_hi:[1,0,0]
	s_nop 0
	v_mul_f32_e32 v53, 0x4b800000, v59
	v_cmp_gt_f32_e32 vcc, s1, v59
	v_mul_f32_e32 v60, 0x4b800000, v58
	v_cmp_gt_f32_e64 s[2:3], s1, v58
	v_cndmask_b32_e32 v53, v59, v53, vcc
	v_rsq_f32_e32 v53, v53
	v_cndmask_b32_e64 v58, v58, v60, s[2:3]
	v_rsq_f32_e32 v60, v58
	v_lshl_add_u64 v[58:59], s[16:17], 0, v[36:37]
	v_mul_f32_e32 v61, 0x45800000, v53
	v_cndmask_b32_e32 v53, v53, v61, vcc
	v_mul_f32_e32 v30, v30, v53
	v_mul_f32_e32 v32, v32, v53
	v_mul_f32_e32 v31, v31, v53
	v_mul_f32_e32 v33, v33, v53
	v_mul_f32_e32 v30, v88, v30
	v_mul_f32_e32 v32, v90, v32
	v_mul_f32_e32 v62, 0x45800000, v60
	v_mul_f32_e32 v31, v89, v31
	v_mul_f32_e32 v33, v91, v33
	v_bfe_u32 v61, v30, 16, 1
	v_bfe_u32 v63, v32, 16, 1
	v_cndmask_b32_e64 v60, v60, v62, s[2:3]
	v_bfe_u32 v62, v31, 16, 1
	v_bfe_u32 v64, v33, 16, 1
	v_add3_u32 v30, v30, v61, s28
	v_add3_u32 v32, v32, v63, s28
	v_add3_u32 v31, v31, v62, s28
	v_add3_u32 v33, v33, v64, s28
	v_lshrrev_b32_e32 v30, 16, v30
	v_lshrrev_b32_e32 v32, 16, v32
	v_and_or_b32 v30, v31, s5, v30
	v_and_or_b32 v31, v33, s5, v32
	v_add_co_u32_e32 v32, vcc, s29, v44
	v_mul_f32_e32 v26, v26, v60
	s_nop 0
	v_addc_co_u32_e32 v33, vcc, 0, v45, vcc
	v_mul_f32_e32 v26, v88, v26
	v_mul_f32_e32 v27, v27, v60
	global_store_dwordx2 v[32:33], v[30:31], off
	v_mul_f32_e32 v27, v89, v27
	v_bfe_u32 v30, v26, 16, 1
	v_add3_u32 v26, v26, v30, s28
	v_bfe_u32 v30, v27, 16, 1
	v_lshrrev_b32_e32 v26, 16, v26
	v_add3_u32 v27, v27, v30, s28
	v_and_or_b32 v26, v27, s5, v26
	v_mul_f32_e32 v27, v28, v60
	v_mul_f32_e32 v27, v90, v27
	v_mul_f32_e32 v28, v29, v60
	v_mul_f32_e32 v28, v91, v28
	v_bfe_u32 v29, v27, 16, 1
	v_add3_u32 v27, v27, v29, s28
	v_bfe_u32 v29, v28, 16, 1
	v_lshrrev_b32_e32 v27, 16, v27
	v_add3_u32 v28, v28, v29, s28
	v_add_co_u32_e32 v30, vcc, s29, v58
	v_and_or_b32 v27, v28, s5, v27
	s_nop 0
	v_addc_co_u32_e32 v31, vcc, 0, v59, vcc
	global_store_dwordx2 v[30:31], v[26:27], off
	v_mul_f32_e32 v22, v22, v53
	v_mul_f32_e32 v24, v24, v53
	v_mul_f32_e32 v23, v23, v53
	v_mul_f32_e32 v25, v25, v53
	v_mul_f32_e32 v18, v18, v60
	v_mul_f32_e32 v19, v19, v60
	v_mul_f32_e32 v20, v20, v60
	v_mul_f32_e32 v21, v21, v60
	v_mul_f32_e32 v14, v14, v53
	v_mul_f32_e32 v16, v16, v53
	v_mul_f32_e32 v15, v15, v53
	v_mul_f32_e32 v17, v17, v53
	v_mul_f32_e32 v10, v10, v60
	v_mul_f32_e32 v11, v11, v60
	v_mul_f32_e32 v12, v12, v60
	v_mul_f32_e32 v13, v13, v60
	v_mul_f32_e32 v6, v6, v53
	v_mul_f32_e32 v8, v8, v53
	v_pk_mul_f32 v[2:3], v[2:3], v[60:61] op_sel_hi:[1,0]
	v_mul_f32_e32 v7, v7, v53
	v_mul_f32_e32 v9, v9, v53
	v_pk_mul_f32 v[4:5], v[4:5], v[60:61] op_sel_hi:[1,0]
	s_lshl_b64 s[2:3], s[26:27], 10
	v_mul_f32_e32 v22, v22, v92
	v_mul_f32_e32 v24, v24, v94
	v_mul_f32_e32 v23, v23, v93
	v_mul_f32_e32 v25, v25, v95
	v_mul_f32_e32 v18, v92, v18
	v_mul_f32_e32 v19, v93, v19
	v_mul_f32_e32 v20, v94, v20
	v_bfe_u32 v26, v22, 16, 1
	v_bfe_u32 v28, v24, 16, 1
	v_mul_f32_e32 v21, v95, v21
	v_bfe_u32 v27, v23, 16, 1
	v_bfe_u32 v29, v25, 16, 1
	v_bfe_u32 v44, v18, 16, 1
	v_bfe_u32 v45, v19, 16, 1
	v_bfe_u32 v54, v20, 16, 1
	v_add3_u32 v22, v22, v26, s28
	v_add3_u32 v24, v24, v28, s28
	v_bfe_u32 v55, v21, 16, 1
	v_add3_u32 v23, v23, v27, s28
	v_add3_u32 v25, v25, v29, s28
	v_add3_u32 v18, v18, v44, s28
	v_add3_u32 v26, v19, v45, s28
	v_add3_u32 v19, v20, v54, s28
	v_lshrrev_b32_e32 v20, 16, v22
	v_lshrrev_b32_e32 v22, 16, v24
	v_add3_u32 v21, v21, v55, s28
	v_lshrrev_b32_e32 v24, 16, v18
	v_lshrrev_b32_e32 v27, 16, v19
	v_and_or_b32 v18, v23, s5, v20
	v_and_or_b32 v19, v25, s5, v22
	v_and_or_b32 v20, v26, s5, v24
	v_and_or_b32 v21, v21, s5, v27
	global_store_dwordx2 v[32:33], v[18:19], off offset:512
	global_store_dwordx2 v[30:31], v[20:21], off offset:512
	v_mul_f32_e32 v14, v14, v96
	v_mul_f32_e32 v16, v16, v98
	v_mul_f32_e32 v15, v15, v97
	v_mul_f32_e32 v17, v17, v99
	v_mul_f32_e32 v10, v96, v10
	v_mul_f32_e32 v11, v97, v11
	v_mul_f32_e32 v12, v98, v12
	v_bfe_u32 v18, v14, 16, 1
	v_bfe_u32 v20, v16, 16, 1
	v_mul_f32_e32 v13, v99, v13
	v_bfe_u32 v19, v15, 16, 1
	v_bfe_u32 v21, v17, 16, 1
	v_bfe_u32 v22, v10, 16, 1
	v_bfe_u32 v23, v11, 16, 1
	v_bfe_u32 v24, v12, 16, 1
	v_add3_u32 v14, v14, v18, s28
	v_add3_u32 v16, v16, v20, s28
	v_bfe_u32 v25, v13, 16, 1
	v_add3_u32 v15, v15, v19, s28
	v_add3_u32 v17, v17, v21, s28
	v_add3_u32 v10, v10, v22, s28
	v_add3_u32 v18, v11, v23, s28
	v_add3_u32 v11, v12, v24, s28
	v_lshrrev_b32_e32 v12, 16, v14
	v_lshrrev_b32_e32 v14, 16, v16
	v_add3_u32 v13, v13, v25, s28
	v_lshrrev_b32_e32 v16, 16, v10
	v_lshrrev_b32_e32 v19, 16, v11
	v_and_or_b32 v10, v15, s5, v12
	v_and_or_b32 v11, v17, s5, v14
	v_and_or_b32 v12, v18, s5, v16
	v_and_or_b32 v13, v13, s5, v19
	global_store_dwordx2 v[32:33], v[10:11], off offset:1024
	global_store_dwordx2 v[30:31], v[12:13], off offset:1024
	v_mul_f32_e32 v6, v6, v100
	v_mul_f32_e32 v8, v8, v102
	v_pk_mul_f32 v[2:3], v[2:3], v[100:101]
	v_mul_f32_e32 v7, v7, v101
	v_mul_f32_e32 v9, v9, v103
	v_bfe_u32 v10, v6, 16, 1
	v_bfe_u32 v14, v8, 16, 1
	v_and_b32_sdwa v17, v2, v52 dst_sel:DWORD dst_unused:UNUSED_PAD src0_sel:WORD_1 src1_sel:DWORD
	v_bfe_u32 v11, v7, 16, 1
	v_bfe_u32 v15, v9, 16, 1
	v_and_b32_sdwa v16, v3, v52 dst_sel:DWORD dst_unused:UNUSED_PAD src0_sel:WORD_1 src1_sel:DWORD
	v_add3_u32 v6, v6, v10, s28
	v_add3_u32 v8, v8, v14, s28
	v_add3_u32 v2, v2, v17, s28
	v_add3_u32 v7, v7, v11, s28
	v_add3_u32 v9, v9, v15, s28
	v_add3_u32 v3, v3, v16, s28
	v_lshrrev_b32_e32 v6, 16, v6
	v_lshrrev_b32_e32 v8, 16, v8
	v_lshrrev_b32_e32 v2, 16, v2
	v_and_or_b32 v6, v7, s5, v6
	v_and_or_b32 v7, v9, s5, v8
	v_and_or_b32 v2, v3, s5, v2
	v_pk_mul_f32 v[4:5], v[4:5], v[102:103]
	global_store_dwordx2 v[32:33], v[6:7], off offset:1536
	s_branch .LBB0_44
